# removed the workgroup barrier before each work-queue pop (units have internal barriers that already order the slot word)
# speedup vs baseline: 1.0057x; 1.0057x over previous
; #define LAS __attribute__((address_space(3)))
; __global__ void __launch_bounds__(512) fwd_megakernel(Args a) {
;     ...
;             int qo_ = LDSCTL_OFF + 64; asm volatile("" : "+s"(qo_)); volatile LAS int* qslot = (volatile LAS int*)(lds + qo_);
;             int tq0_ = threadIdx.x; asm volatile("" : "+v"(tq0_));
;             __syncthreads();
;             if (tq0_ == 0) { int slot = -1;
;                 while (tries < 8) { int len = (myq < 4) ? 64 : 192;
;     ...
;                     if (rep) len = 64;
;     ...
;                     if (rep) { if (myq < 4) len = 0; }
;     ...
;  const int idx = (int)atomicAdd(barw + BAR_QCTR + 64 * myq, 1u);
;     ...
;                     if (rep && myq >= 4 && idx < 64) continue;
;     ...
;                     if (idx < len) { slot = (myq << 16) | idx; break; } myq = (myq + 1) & 7; ++tries; }
;                 qslot[0] = slot; }
.LBB0_345:
.LBB0_346:
	s_mov_b32 s4, 0x21040
	v_mov_b32_e32 v0, v236
	s_nop 0
	v_cmp_eq_u32_e32 vcc, 0, v0
	s_nop 0
	s_and_saveexec_b64 s[0:1], vcc
	s_cbranch_execz .LBB0_356
	v_mov_b32_e32 v2, -1
	s_mov_b64 s[6:7], 0
	s_branch .LBB0_350
